# v045 with attention-A step reordered: LDS-independent exp/sum/pack block first (hides K-fragment latency), single waits, cross-half max combine only in the rare rescale path
# baseline (speedup 1.0000x reference)
.LBB0_496:
	v_ashrrev_i32_e32 v191, 31, v190
	v_lshlrev_b32_e32 v207, 2, v168
	s_waitcnt lgkmcnt(7)
	v_mfma_f32_32x32x16_bf16 v[66:81], v[162:165], v[130:133], v[34:49]
	v_exp_f32_e32 v65, v98
	v_exp_f32_e32 v162, v99
	s_nop 0
	v_cvt_pk_bf16_f32 v98, v65, v162
	v_add_f32_e32 v65, 0, v65
	v_add_f32_e32 v65, v162, v65
	s_waitcnt lgkmcnt(5)
	v_mfma_f32_32x32x16_bf16 v[34:49], v[158:161], v[130:133], v[34:49]
	v_exp_f32_e32 v158, v100
	v_exp_f32_e32 v159, v101
	v_add_f32_e32 v65, v158, v65
	v_cvt_pk_bf16_f32 v99, v158, v159
	v_add_f32_e32 v65, v159, v65
	v_mfma_f32_32x32x16_bf16 v[66:81], v[154:157], v[134:137], v[66:81]
	v_exp_f32_e32 v154, v102
	v_exp_f32_e32 v155, v103
	v_add_f32_e32 v65, v154, v65
	v_cvt_pk_bf16_f32 v100, v154, v155
	v_add_f32_e32 v65, v155, v65
	s_waitcnt lgkmcnt(3)
	v_mfma_f32_32x32x16_bf16 v[66:81], v[126:129], v[138:141], v[66:81]
	v_exp_f32_e32 v104, v104
	v_exp_f32_e32 v105, v105
	v_add_f32_e32 v65, v104, v65
	v_cvt_pk_bf16_f32 v101, v104, v105
	v_add_f32_e32 v65, v105, v65
	s_waitcnt lgkmcnt(2)
	v_mfma_f32_32x32x16_bf16 v[66:81], v[122:125], v[142:145], v[66:81]
	v_exp_f32_e32 v106, v106
	v_exp_f32_e32 v107, v107
	s_nop 0
	v_cvt_pk_bf16_f32 v102, v106, v107
	v_exp_f32_e32 v108, v108
	v_mfma_f32_32x32x16_bf16 v[34:49], v[60:63], v[134:137], v[34:49]
	v_exp_f32_e32 v109, v109
	v_add_f32_e32 v60, v106, v65
	v_add_f32_e32 v60, v107, v60
	v_add_f32_e32 v60, v108, v60
	v_cvt_pk_bf16_f32 v103, v108, v109
	v_exp_f32_e32 v110, v110
	v_exp_f32_e32 v111, v111
	s_waitcnt lgkmcnt(1)
	v_mfma_f32_32x32x16_bf16 v[34:49], v[56:59], v[138:141], v[34:49]
	v_add_f32_e32 v60, v109, v60
	v_add_f32_e32 v60, v110, v60
	v_cvt_pk_bf16_f32 v104, v110, v111
	v_exp_f32_e32 v112, v112
	v_exp_f32_e32 v162, v113
	v_add_f32_e32 v60, v111, v60
	v_add_f32_e32 v65, v112, v60
	v_cvt_pk_bf16_f32 v105, v112, v162
	s_setprio 0
	ds_read_b128 v[56:59], v64 offset:27648
	ds_read_b128 v[60:63], v64 offset:27680
	ds_read_b128 v[106:109], v64 offset:27712
	ds_read_b128 v[110:113], v64 offset:27744
	ds_read_b128 v[122:125], v64 offset:32256
	ds_read_b128 v[126:129], v64 offset:32288
	ds_read_b128 v[154:157], v64 offset:32320
	ds_read_b128 v[158:161], v64 offset:32352
	v_add_f32_e32 v64, v162, v65
	v_exp_f32_e32 v65, v82
	v_exp_f32_e32 v82, v83
	v_exp_f32_e32 v83, v84
	v_exp_f32_e32 v84, v85
	v_add_f32_e32 v64, v65, v64
	v_exp_f32_e32 v85, v86
	v_add_f32_e32 v64, v82, v64
	v_exp_f32_e32 v86, v87
	v_add_f32_e32 v64, v83, v64
	v_exp_f32_e32 v87, v88
	v_add_f32_e32 v64, v84, v64
	v_exp_f32_e32 v88, v89
	v_add_f32_e32 v64, v85, v64
	v_exp_f32_e32 v89, v90
	v_add_f32_e32 v64, v86, v64
	v_exp_f32_e32 v90, v91
	v_add_f32_e32 v64, v87, v64
	v_exp_f32_e32 v91, v92
	v_add_f32_e32 v64, v88, v64
	v_exp_f32_e32 v92, v93
	v_add_f32_e32 v64, v89, v64
	v_exp_f32_e32 v93, v94
	v_add_f32_e32 v64, v90, v64
	v_exp_f32_e32 v94, v95
	v_add_f32_e32 v64, v91, v64
	v_exp_f32_e32 v95, v96
	v_add_f32_e32 v64, v92, v64
	v_exp_f32_e32 v96, v97
	v_add_f32_e32 v64, v93, v64
	v_add_f32_e32 v64, v94, v64
	v_add_f32_e32 v64, v95, v64
	v_add_f32_e32 v64, v96, v64
	v_cvt_pk_bf16_f32 v82, v65, v82
	v_cvt_pk_bf16_f32 v83, v83, v84
	v_cvt_pk_bf16_f32 v84, v85, v86
	v_cvt_pk_bf16_f32 v85, v87, v88
	v_cvt_pk_bf16_f32 v86, v89, v90
	v_cvt_pk_bf16_f32 v87, v91, v92
	v_cvt_pk_bf16_f32 v88, v93, v94
	v_cvt_pk_bf16_f32 v89, v95, v96
	s_setprio 1
	s_waitcnt lgkmcnt(7)
	v_mfma_f32_32x32x16_bf16 v[18:33], v[56:59], v[98:101], v[18:33]
	v_add_f32_e32 v210, v50, v64
	s_waitcnt lgkmcnt(3)
	v_mfma_f32_32x32x16_bf16 v[2:17], v[122:125], v[98:101], v[2:17]
	v_mfma_f32_32x32x16_bf16 v[18:33], v[60:63], v[102:105], v[18:33]
	s_waitcnt lgkmcnt(2)
	v_mfma_f32_32x32x16_bf16 v[2:17], v[126:129], v[102:105], v[2:17]
	v_mfma_f32_32x32x16_bf16 v[18:33], v[106:109], v[82:85], v[18:33]
	s_waitcnt lgkmcnt(1)
	v_mfma_f32_32x32x16_bf16 v[2:17], v[154:157], v[82:85], v[2:17]
	v_mfma_f32_32x32x16_bf16 v[18:33], v[110:113], v[86:89], v[18:33]
	s_waitcnt lgkmcnt(0)
	v_mfma_f32_32x32x16_bf16 v[2:17], v[158:161], v[86:89], v[2:17]
	v_mfma_f32_32x32x16_bf16 v[34:49], v[52:55], v[142:145], v[34:49]
	s_setprio 0
	s_movk_i32 s2, 0x4800
	s_mov_b32 s3, 0
	s_mov_b32 s0, 0x9000
	s_mov_b32 s10, 6
	v_mov_b32_e32 v50, v51
	v_mov_b32_e32 v52, v51
	v_mov_b32_e32 v53, v51
	v_mov_b32_e32 v54, v51
	v_mov_b32_e32 v55, v51
	v_mov_b32_e32 v56, v51
	v_mov_b32_e32 v57, v51
	v_mov_b32_e32 v58, v51
	v_mov_b32_e32 v59, v51
	v_mov_b32_e32 v60, v51
	v_mov_b32_e32 v61, v51
	v_mov_b32_e32 v62, v51
	v_mov_b32_e32 v63, v51
	v_mov_b32_e32 v64, v51
	v_mov_b32_e32 v65, v51
	s_waitcnt vmcnt(3)
	ds_write_b128 v169, v[114:117]
	s_waitcnt vmcnt(2)
	ds_write_b128 v170, v[118:121] offset:9216
	v_max3_f32 v248, v66, v67, v68
	v_max3_f32 v249, v34, v35, v36
	v_max3_f32 v248, v248, v69, v70
	v_max3_f32 v249, v249, v37, v38
	v_max3_f32 v248, v248, v71, v72
	v_max3_f32 v249, v249, v39, v40
	v_max3_f32 v248, v248, v73, v74
	v_max3_f32 v249, v249, v41, v42
	v_max3_f32 v248, v248, v75, v76
	v_max3_f32 v249, v249, v43, v44
	v_max3_f32 v248, v248, v77, v78
	v_max3_f32 v249, v249, v45, v46
	v_max3_f32 v248, v248, v79, v80
	v_max3_f32 v249, v249, v47, v48
	v_max_f32_e32 v248, v248, v81
	v_max_f32_e32 v249, v249, v49
	v_max_f32_e32 v248, v248, v249
	v_cmp_lt_f32_e32 vcc, 4.0, v248
	s_cbranch_vccnz .Lattn_resc_pre
.LBB0_497:
	s_add_i32 s11, s10, -1
	s_min_i32 s1, s11, s58
	s_lshl_b32 s44, s1, 6
	s_ashr_i32 s45, s44, 31
	v_mad_i64_i32 v[200:201], s[46:47], s1, v239, v[194:195]
	v_lshl_add_u64 v[236:237], s[44:45], 1, v[208:209]
	s_mov_b32 s12, s3
	s_mov_b32 s3, s0
	s_add_i32 s15, s12, 0
	s_add_i32 s24, s10, -2
	s_cmp_lt_u32 s24, s16
	s_cselect_b64 s[0:1], -1, 0
	s_add_i32 s23, s3, 0
	s_waitcnt lgkmcnt(0)
	s_barrier
	v_add_u32_e32 v252, s15, v193
	ds_read_b128 v[162:165], v252
	ds_read_b128 v[178:181], v252 offset:4608
	ds_read_b128 v[166:169], v252 offset:32
	ds_read_b128 v[182:185], v252 offset:4640
	ds_read_b128 v[170:173], v252 offset:64
	ds_read_b128 v[186:189], v252 offset:4672
	ds_read_b128 v[174:177], v252 offset:96
	ds_read_b128 v[82:85], v252 offset:4704
	global_load_dwordx4 v[154:157], v[200:201], off offset:1024
	global_load_dwordx4 v[158:161], v[236:237], off
	v_add_u32_e32 v253, s23, v0
	v_exp_f32_e32 v66, v66
	v_exp_f32_e32 v67, v67
	v_exp_f32_e32 v68, v68
	v_exp_f32_e32 v69, v69
	v_add_f32_e32 v246, v66, v67
	v_cvt_pk_bf16_f32 v66, v66, v67
	v_exp_f32_e32 v70, v70
	v_exp_f32_e32 v71, v71
	v_add_f32_e32 v246, v68, v246
	v_add_f32_e32 v246, v69, v246
	v_cvt_pk_bf16_f32 v67, v68, v69
	v_exp_f32_e32 v72, v72
	v_exp_f32_e32 v73, v73
	v_add_f32_e32 v246, v70, v246
	v_add_f32_e32 v246, v71, v246
	v_cvt_pk_bf16_f32 v68, v70, v71
	v_exp_f32_e32 v74, v74
	v_exp_f32_e32 v75, v75
	v_add_f32_e32 v246, v72, v246
	v_add_f32_e32 v246, v73, v246
	v_cvt_pk_bf16_f32 v69, v72, v73
	v_exp_f32_e32 v76, v76
	v_exp_f32_e32 v77, v77
	v_add_f32_e32 v246, v74, v246
	v_add_f32_e32 v246, v75, v246
	v_cvt_pk_bf16_f32 v70, v74, v75
	s_waitcnt lgkmcnt(0)
	v_mfma_f32_32x32x16_bf16 v[114:129], v[162:165], v[130:133], v[50:65]
	ds_read_b128 v[86:89], v253 offset:9216
	ds_read_b128 v[216:219], v253 offset:13824
	v_exp_f32_e32 v78, v78
	v_exp_f32_e32 v79, v79
	v_add_f32_e32 v246, v76, v246
	v_add_f32_e32 v246, v77, v246
	v_cvt_pk_bf16_f32 v71, v76, v77
	v_mfma_f32_32x32x16_bf16 v[98:113], v[178:181], v[130:133], v[50:65]
	ds_read_b128 v[90:93], v253 offset:9248
	ds_read_b128 v[220:223], v253 offset:13856
	v_exp_f32_e32 v80, v80
	v_exp_f32_e32 v81, v81
	v_add_f32_e32 v246, v78, v246
	v_add_f32_e32 v246, v79, v246
	v_cvt_pk_bf16_f32 v72, v78, v79
	v_mfma_f32_32x32x16_bf16 v[114:129], v[166:169], v[134:137], v[114:129]
	ds_read_b128 v[94:97], v253 offset:9280
	ds_read_b128 v[224:227], v253 offset:13888
	v_exp_f32_e32 v34, v34
	v_exp_f32_e32 v35, v35
	v_add_f32_e32 v246, v80, v246
	v_add_f32_e32 v246, v81, v246
	v_cvt_pk_bf16_f32 v73, v80, v81
	v_mfma_f32_32x32x16_bf16 v[98:113], v[182:185], v[134:137], v[98:113]
	ds_read_b128 v[212:215], v253 offset:9312
	ds_read_b128 v[242:245], v253 offset:13920
	v_exp_f32_e32 v36, v36
	v_exp_f32_e32 v37, v37
	v_add_f32_e32 v247, v34, v35
	v_cvt_pk_bf16_f32 v74, v34, v35
	v_mfma_f32_32x32x16_bf16 v[114:129], v[170:173], v[138:141], v[114:129]
	v_exp_f32_e32 v38, v38
	v_exp_f32_e32 v39, v39
	v_add_f32_e32 v247, v36, v247
	v_add_f32_e32 v247, v37, v247
	v_cvt_pk_bf16_f32 v75, v36, v37
	v_mfma_f32_32x32x16_bf16 v[98:113], v[186:189], v[138:141], v[98:113]
	v_exp_f32_e32 v40, v40
	v_exp_f32_e32 v41, v41
	v_add_f32_e32 v247, v38, v247
	v_add_f32_e32 v247, v39, v247
	v_cvt_pk_bf16_f32 v76, v38, v39
	v_mfma_f32_32x32x16_bf16 v[114:129], v[174:177], v[142:145], v[114:129]
	v_exp_f32_e32 v42, v42
	v_exp_f32_e32 v43, v43
	v_add_f32_e32 v247, v40, v247
	v_add_f32_e32 v247, v41, v247
	v_cvt_pk_bf16_f32 v77, v40, v41
	v_mfma_f32_32x32x16_bf16 v[98:113], v[82:85], v[142:145], v[98:113]
	v_exp_f32_e32 v44, v44
	v_exp_f32_e32 v45, v45
	v_add_f32_e32 v247, v42, v247
	v_add_f32_e32 v247, v43, v247
	v_cvt_pk_bf16_f32 v78, v42, v43
	s_waitcnt lgkmcnt(0)
	v_mfma_f32_32x32x16_bf16 v[18:33], v[86:89], v[66:69], v[18:33]
	v_exp_f32_e32 v46, v46
	v_exp_f32_e32 v47, v47
	v_add_f32_e32 v247, v44, v247
	v_add_f32_e32 v247, v45, v247
	v_cvt_pk_bf16_f32 v79, v44, v45
	v_mfma_f32_32x32x16_bf16 v[2:17], v[216:219], v[66:69], v[2:17]
	v_exp_f32_e32 v48, v48
	v_exp_f32_e32 v49, v49
	v_add_f32_e32 v247, v46, v247
	v_add_f32_e32 v247, v47, v247
	v_cvt_pk_bf16_f32 v80, v46, v47
	v_mfma_f32_32x32x16_bf16 v[18:33], v[90:93], v[70:73], v[18:33]
	v_add_f32_e32 v247, v48, v247
	v_add_f32_e32 v247, v49, v247
	v_cvt_pk_bf16_f32 v81, v48, v49
	v_max3_f32 v248, v114, v115, v116
	v_max3_f32 v249, v98, v99, v100
	v_mfma_f32_32x32x16_bf16 v[2:17], v[220:223], v[70:73], v[2:17]
	v_max3_f32 v248, v248, v117, v118
	v_max3_f32 v249, v249, v101, v102
	v_max3_f32 v248, v248, v119, v120
	v_mfma_f32_32x32x16_bf16 v[18:33], v[94:97], v[74:77], v[18:33]
	v_max3_f32 v249, v249, v103, v104
	v_max3_f32 v248, v248, v121, v122
	v_max3_f32 v249, v249, v105, v106
	v_mfma_f32_32x32x16_bf16 v[2:17], v[224:227], v[74:77], v[2:17]
	v_max3_f32 v248, v248, v123, v124
	v_max3_f32 v249, v249, v107, v108
	v_max3_f32 v248, v248, v125, v126
	v_mfma_f32_32x32x16_bf16 v[18:33], v[212:215], v[78:81], v[18:33]
	v_max3_f32 v249, v249, v109, v110
	v_max3_f32 v248, v248, v127, v128
	v_max3_f32 v249, v249, v111, v112
	v_mfma_f32_32x32x16_bf16 v[2:17], v[242:245], v[78:81], v[2:17]
	v_max_f32_e32 v248, v248, v129
	v_max_f32_e32 v249, v249, v113
	v_add_f32_e32 v210, v210, v246
	v_add_f32_e32 v210, v210, v247
	s_cmp_ge_u32 s24, s16
	s_cbranch_scc1 .Lattn_skipw1
	s_add_i32 s24, s2, 0
	v_add_u32_e32 v200, s24, v192
	v_add_u32_e32 v201, s24, v204
	s_waitcnt vmcnt(3)
	ds_write_b128 v200, v[146:149]
	s_waitcnt vmcnt(2)
	ds_write_b128 v201, v[150:153] offset:9216
.Lattn_skipw1:
	v_max_f32_e32 v248, v248, v249
	v_cmp_lt_f32_e32 vcc, 4.0, v248
	s_cbranch_vccnz .Lattn_resc_h1
.Lattn_cont_h1:
	s_min_i32 s24, s10, s58
	s_lshl_b32 s44, s24, 6
	s_ashr_i32 s45, s44, 31
	v_mad_i64_i32 v[200:201], s[46:47], s24, v239, v[194:195]
	v_lshl_add_u64 v[236:237], s[44:45], 1, v[208:209]
	s_waitcnt lgkmcnt(0)
	s_barrier
	v_add_u32_e32 v252, s2, v205
	ds_read_b128 v[162:165], v252
	ds_read_b128 v[178:181], v252 offset:4608
	ds_read_b128 v[166:169], v252 offset:32
	ds_read_b128 v[182:185], v252 offset:4640
	ds_read_b128 v[170:173], v252 offset:64
	ds_read_b128 v[186:189], v252 offset:4672
	ds_read_b128 v[174:177], v252 offset:96
	ds_read_b128 v[82:85], v252 offset:4704
	global_load_dwordx4 v[146:149], v[200:201], off offset:1024
	global_load_dwordx4 v[150:153], v[236:237], off
	v_add_u32_e32 v253, s15, v0
	v_exp_f32_e32 v114, v114
	v_exp_f32_e32 v115, v115
	v_exp_f32_e32 v116, v116
	v_exp_f32_e32 v117, v117
	v_add_f32_e32 v246, v114, v115
	v_cvt_pk_bf16_f32 v114, v114, v115
	v_exp_f32_e32 v118, v118
	v_exp_f32_e32 v119, v119
	v_add_f32_e32 v246, v116, v246
	v_add_f32_e32 v246, v117, v246
	v_cvt_pk_bf16_f32 v115, v116, v117
	v_exp_f32_e32 v120, v120
	v_exp_f32_e32 v121, v121
	v_add_f32_e32 v246, v118, v246
	v_add_f32_e32 v246, v119, v246
	v_cvt_pk_bf16_f32 v116, v118, v119
	v_exp_f32_e32 v122, v122
	v_exp_f32_e32 v123, v123
	v_add_f32_e32 v246, v120, v246
	v_add_f32_e32 v246, v121, v246
	v_cvt_pk_bf16_f32 v117, v120, v121
	v_exp_f32_e32 v124, v124
	v_exp_f32_e32 v125, v125
	v_add_f32_e32 v246, v122, v246
	v_add_f32_e32 v246, v123, v246
	v_cvt_pk_bf16_f32 v118, v122, v123
	s_waitcnt lgkmcnt(0)
	v_mfma_f32_32x32x16_bf16 v[66:81], v[162:165], v[130:133], v[50:65]
	ds_read_b128 v[86:89], v253 offset:9216
	ds_read_b128 v[216:219], v253 offset:13824
	v_exp_f32_e32 v126, v126
	v_exp_f32_e32 v127, v127
	v_add_f32_e32 v246, v124, v246
	v_add_f32_e32 v246, v125, v246
	v_cvt_pk_bf16_f32 v119, v124, v125
	v_mfma_f32_32x32x16_bf16 v[34:49], v[178:181], v[130:133], v[50:65]
	ds_read_b128 v[90:93], v253 offset:9248
	ds_read_b128 v[220:223], v253 offset:13856
	v_exp_f32_e32 v128, v128
	v_exp_f32_e32 v129, v129
	v_add_f32_e32 v246, v126, v246
	v_add_f32_e32 v246, v127, v246
	v_cvt_pk_bf16_f32 v120, v126, v127
	v_mfma_f32_32x32x16_bf16 v[66:81], v[166:169], v[134:137], v[66:81]
	ds_read_b128 v[94:97], v253 offset:9280
	ds_read_b128 v[224:227], v253 offset:13888
	v_exp_f32_e32 v98, v98
	v_exp_f32_e32 v99, v99
	v_add_f32_e32 v246, v128, v246
	v_add_f32_e32 v246, v129, v246
	v_cvt_pk_bf16_f32 v121, v128, v129
	v_mfma_f32_32x32x16_bf16 v[34:49], v[182:185], v[134:137], v[34:49]
	ds_read_b128 v[212:215], v253 offset:9312
	ds_read_b128 v[242:245], v253 offset:13920
	v_exp_f32_e32 v100, v100
	v_exp_f32_e32 v101, v101
	v_add_f32_e32 v247, v98, v99
	v_cvt_pk_bf16_f32 v122, v98, v99
	v_mfma_f32_32x32x16_bf16 v[66:81], v[170:173], v[138:141], v[66:81]
	v_exp_f32_e32 v102, v102
	v_exp_f32_e32 v103, v103
	v_add_f32_e32 v247, v100, v247
	v_add_f32_e32 v247, v101, v247
	v_cvt_pk_bf16_f32 v123, v100, v101
	v_mfma_f32_32x32x16_bf16 v[34:49], v[186:189], v[138:141], v[34:49]
	v_exp_f32_e32 v104, v104
	v_exp_f32_e32 v105, v105
	v_add_f32_e32 v247, v102, v247
	v_add_f32_e32 v247, v103, v247
	v_cvt_pk_bf16_f32 v124, v102, v103
	v_mfma_f32_32x32x16_bf16 v[66:81], v[174:177], v[142:145], v[66:81]
	v_exp_f32_e32 v106, v106
	v_exp_f32_e32 v107, v107
	v_add_f32_e32 v247, v104, v247
	v_add_f32_e32 v247, v105, v247
	v_cvt_pk_bf16_f32 v125, v104, v105
	v_mfma_f32_32x32x16_bf16 v[34:49], v[82:85], v[142:145], v[34:49]
	v_exp_f32_e32 v108, v108
	v_exp_f32_e32 v109, v109
	v_add_f32_e32 v247, v106, v247
	v_add_f32_e32 v247, v107, v247
	v_cvt_pk_bf16_f32 v126, v106, v107
	s_waitcnt lgkmcnt(0)
	v_mfma_f32_32x32x16_bf16 v[18:33], v[86:89], v[114:117], v[18:33]
	v_exp_f32_e32 v110, v110
	v_exp_f32_e32 v111, v111
	v_add_f32_e32 v247, v108, v247
	v_add_f32_e32 v247, v109, v247
	v_cvt_pk_bf16_f32 v127, v108, v109
	v_mfma_f32_32x32x16_bf16 v[2:17], v[216:219], v[114:117], v[2:17]
	v_exp_f32_e32 v112, v112
	v_exp_f32_e32 v113, v113
	v_add_f32_e32 v247, v110, v247
	v_add_f32_e32 v247, v111, v247
	v_cvt_pk_bf16_f32 v128, v110, v111
	v_mfma_f32_32x32x16_bf16 v[18:33], v[90:93], v[118:121], v[18:33]
	v_add_f32_e32 v247, v112, v247
	v_add_f32_e32 v247, v113, v247
	v_cvt_pk_bf16_f32 v129, v112, v113
	v_max3_f32 v248, v66, v67, v68
	v_max3_f32 v249, v34, v35, v36
	v_mfma_f32_32x32x16_bf16 v[2:17], v[220:223], v[118:121], v[2:17]
	v_max3_f32 v248, v248, v69, v70
	v_max3_f32 v249, v249, v37, v38
	v_max3_f32 v248, v248, v71, v72
	v_mfma_f32_32x32x16_bf16 v[18:33], v[94:97], v[122:125], v[18:33]
	v_max3_f32 v249, v249, v39, v40
	v_max3_f32 v248, v248, v73, v74
	v_max3_f32 v249, v249, v41, v42
	v_mfma_f32_32x32x16_bf16 v[2:17], v[224:227], v[122:125], v[2:17]
	v_max3_f32 v248, v248, v75, v76
	v_max3_f32 v249, v249, v43, v44
	v_max3_f32 v248, v248, v77, v78
	v_mfma_f32_32x32x16_bf16 v[18:33], v[212:215], v[126:129], v[18:33]
	v_max3_f32 v249, v249, v45, v46
	v_max3_f32 v248, v248, v79, v80
	v_max3_f32 v249, v249, v47, v48
	v_mfma_f32_32x32x16_bf16 v[2:17], v[242:245], v[126:129], v[2:17]
	v_max_f32_e32 v248, v248, v81
	v_max_f32_e32 v249, v249, v49
	v_add_f32_e32 v210, v210, v246
	v_add_f32_e32 v210, v210, v247
	s_cmp_ge_u32 s11, s16
	s_cbranch_scc1 .Lattn_skipw2
	v_add_u32_e32 v200, s23, v192
	v_add_u32_e32 v201, s23, v204
	s_waitcnt vmcnt(3)
	ds_write_b128 v200, v[154:157]
	s_waitcnt vmcnt(2)
	ds_write_b128 v201, v[158:161] offset:9216

.Lattn_resc_pre:
	v_mov_b32_e32 v211, v248
	s_nop 1
	v_permlane32_swap_b32_e32 v248, v211
	v_max_f32_e32 v248, v248, v211
	v_max_f32_e32 v50, 0, v248
	v_exp_f32_e64 v52, -v50
	v_add_f32_e32 v206, v206, v50
	v_pk_add_f32 v[66:67], v[66:67], v[50:51] op_sel_hi:[1,0] neg_lo:[0,1] neg_hi:[0,1]
	v_pk_add_f32 v[68:69], v[68:69], v[50:51] op_sel_hi:[1,0] neg_lo:[0,1] neg_hi:[0,1]
	v_pk_add_f32 v[70:71], v[70:71], v[50:51] op_sel_hi:[1,0] neg_lo:[0,1] neg_hi:[0,1]
	v_pk_add_f32 v[72:73], v[72:73], v[50:51] op_sel_hi:[1,0] neg_lo:[0,1] neg_hi:[0,1]
	v_pk_add_f32 v[74:75], v[74:75], v[50:51] op_sel_hi:[1,0] neg_lo:[0,1] neg_hi:[0,1]
	v_pk_add_f32 v[76:77], v[76:77], v[50:51] op_sel_hi:[1,0] neg_lo:[0,1] neg_hi:[0,1]
	v_pk_add_f32 v[78:79], v[78:79], v[50:51] op_sel_hi:[1,0] neg_lo:[0,1] neg_hi:[0,1]
	v_pk_add_f32 v[80:81], v[80:81], v[50:51] op_sel_hi:[1,0] neg_lo:[0,1] neg_hi:[0,1]
	v_pk_add_f32 v[34:35], v[34:35], v[50:51] op_sel_hi:[1,0] neg_lo:[0,1] neg_hi:[0,1]
	v_pk_add_f32 v[36:37], v[36:37], v[50:51] op_sel_hi:[1,0] neg_lo:[0,1] neg_hi:[0,1]
	v_pk_add_f32 v[38:39], v[38:39], v[50:51] op_sel_hi:[1,0] neg_lo:[0,1] neg_hi:[0,1]
	v_pk_add_f32 v[40:41], v[40:41], v[50:51] op_sel_hi:[1,0] neg_lo:[0,1] neg_hi:[0,1]
	v_pk_add_f32 v[42:43], v[42:43], v[50:51] op_sel_hi:[1,0] neg_lo:[0,1] neg_hi:[0,1]
	v_pk_add_f32 v[44:45], v[44:45], v[50:51] op_sel_hi:[1,0] neg_lo:[0,1] neg_hi:[0,1]
	v_pk_add_f32 v[46:47], v[46:47], v[50:51] op_sel_hi:[1,0] neg_lo:[0,1] neg_hi:[0,1]
	v_pk_add_f32 v[48:49], v[48:49], v[50:51] op_sel_hi:[1,0] neg_lo:[0,1] neg_hi:[0,1]
	v_pk_mul_f32 v[2:3], v[2:3], v[52:53] op_sel_hi:[1,0]
	v_pk_mul_f32 v[4:5], v[4:5], v[52:53] op_sel_hi:[1,0]
	v_pk_mul_f32 v[6:7], v[6:7], v[52:53] op_sel_hi:[1,0]
	v_pk_mul_f32 v[8:9], v[8:9], v[52:53] op_sel_hi:[1,0]
	v_pk_mul_f32 v[10:11], v[10:11], v[52:53] op_sel_hi:[1,0]
	v_pk_mul_f32 v[12:13], v[12:13], v[52:53] op_sel_hi:[1,0]
	v_pk_mul_f32 v[14:15], v[14:15], v[52:53] op_sel_hi:[1,0]
	v_pk_mul_f32 v[16:17], v[16:17], v[52:53] op_sel_hi:[1,0]
	v_pk_mul_f32 v[18:19], v[18:19], v[52:53] op_sel_hi:[1,0]
	v_pk_mul_f32 v[20:21], v[20:21], v[52:53] op_sel_hi:[1,0]
	v_pk_mul_f32 v[22:23], v[22:23], v[52:53] op_sel_hi:[1,0]
	v_pk_mul_f32 v[24:25], v[24:25], v[52:53] op_sel_hi:[1,0]
	v_pk_mul_f32 v[26:27], v[26:27], v[52:53] op_sel_hi:[1,0]
	v_pk_mul_f32 v[28:29], v[28:29], v[52:53] op_sel_hi:[1,0]
	v_pk_mul_f32 v[30:31], v[30:31], v[52:53] op_sel_hi:[1,0]
	v_pk_mul_f32 v[32:33], v[32:33], v[52:53] op_sel_hi:[1,0]
	v_mul_f32_e32 v210, v210, v52
	v_xor_b32_e32 v50, 0x80000000, v206
	v_mov_b32_e32 v51, v50
	v_mov_b32_e32 v52, v50
	v_mov_b32_e32 v53, v50
	v_mov_b32_e32 v54, v50
	v_mov_b32_e32 v55, v50
	v_mov_b32_e32 v56, v50
	v_mov_b32_e32 v57, v50
	v_mov_b32_e32 v58, v50
	v_mov_b32_e32 v59, v50
	v_mov_b32_e32 v60, v50
	v_mov_b32_e32 v61, v50
	v_mov_b32_e32 v62, v50
	v_mov_b32_e32 v63, v50
	v_mov_b32_e32 v64, v50
	v_mov_b32_e32 v65, v50
	s_branch .LBB0_497
.Lattn_resc_h1:
	v_mov_b32_e32 v211, v248
	s_nop 1
	v_permlane32_swap_b32_e32 v248, v211
	v_max_f32_e32 v248, v248, v211
	v_max_f32_e32 v50, 0, v248
	v_exp_f32_e64 v52, -v50
	v_add_f32_e32 v206, v206, v50
	v_pk_add_f32 v[114:115], v[114:115], v[50:51] op_sel_hi:[1,0] neg_lo:[0,1] neg_hi:[0,1]
	v_pk_add_f32 v[116:117], v[116:117], v[50:51] op_sel_hi:[1,0] neg_lo:[0,1] neg_hi:[0,1]
	v_pk_add_f32 v[118:119], v[118:119], v[50:51] op_sel_hi:[1,0] neg_lo:[0,1] neg_hi:[0,1]
	v_pk_add_f32 v[120:121], v[120:121], v[50:51] op_sel_hi:[1,0] neg_lo:[0,1] neg_hi:[0,1]
	v_pk_add_f32 v[122:123], v[122:123], v[50:51] op_sel_hi:[1,0] neg_lo:[0,1] neg_hi:[0,1]
	v_pk_add_f32 v[124:125], v[124:125], v[50:51] op_sel_hi:[1,0] neg_lo:[0,1] neg_hi:[0,1]
	v_pk_add_f32 v[126:127], v[126:127], v[50:51] op_sel_hi:[1,0] neg_lo:[0,1] neg_hi:[0,1]
	v_pk_add_f32 v[128:129], v[128:129], v[50:51] op_sel_hi:[1,0] neg_lo:[0,1] neg_hi:[0,1]
	v_pk_add_f32 v[98:99], v[98:99], v[50:51] op_sel_hi:[1,0] neg_lo:[0,1] neg_hi:[0,1]
	v_pk_add_f32 v[100:101], v[100:101], v[50:51] op_sel_hi:[1,0] neg_lo:[0,1] neg_hi:[0,1]
	v_pk_add_f32 v[102:103], v[102:103], v[50:51] op_sel_hi:[1,0] neg_lo:[0,1] neg_hi:[0,1]
	v_pk_add_f32 v[104:105], v[104:105], v[50:51] op_sel_hi:[1,0] neg_lo:[0,1] neg_hi:[0,1]
	v_pk_add_f32 v[106:107], v[106:107], v[50:51] op_sel_hi:[1,0] neg_lo:[0,1] neg_hi:[0,1]
	v_pk_add_f32 v[108:109], v[108:109], v[50:51] op_sel_hi:[1,0] neg_lo:[0,1] neg_hi:[0,1]
	v_pk_add_f32 v[110:111], v[110:111], v[50:51] op_sel_hi:[1,0] neg_lo:[0,1] neg_hi:[0,1]
	v_pk_add_f32 v[112:113], v[112:113], v[50:51] op_sel_hi:[1,0] neg_lo:[0,1] neg_hi:[0,1]
	v_pk_mul_f32 v[2:3], v[2:3], v[52:53] op_sel_hi:[1,0]
	v_pk_mul_f32 v[4:5], v[4:5], v[52:53] op_sel_hi:[1,0]
	v_pk_mul_f32 v[6:7], v[6:7], v[52:53] op_sel_hi:[1,0]
	v_pk_mul_f32 v[8:9], v[8:9], v[52:53] op_sel_hi:[1,0]
	v_pk_mul_f32 v[10:11], v[10:11], v[52:53] op_sel_hi:[1,0]
	v_pk_mul_f32 v[12:13], v[12:13], v[52:53] op_sel_hi:[1,0]
	v_pk_mul_f32 v[14:15], v[14:15], v[52:53] op_sel_hi:[1,0]
	v_pk_mul_f32 v[16:17], v[16:17], v[52:53] op_sel_hi:[1,0]
	v_pk_mul_f32 v[18:19], v[18:19], v[52:53] op_sel_hi:[1,0]
	v_pk_mul_f32 v[20:21], v[20:21], v[52:53] op_sel_hi:[1,0]
	v_pk_mul_f32 v[22:23], v[22:23], v[52:53] op_sel_hi:[1,0]
	v_pk_mul_f32 v[24:25], v[24:25], v[52:53] op_sel_hi:[1,0]
	v_pk_mul_f32 v[26:27], v[26:27], v[52:53] op_sel_hi:[1,0]
	v_pk_mul_f32 v[28:29], v[28:29], v[52:53] op_sel_hi:[1,0]
	v_pk_mul_f32 v[30:31], v[30:31], v[52:53] op_sel_hi:[1,0]
	v_pk_mul_f32 v[32:33], v[32:33], v[52:53] op_sel_hi:[1,0]
	v_mul_f32_e32 v210, v210, v52
	v_xor_b32_e32 v50, 0x80000000, v206
	v_mov_b32_e32 v51, v50
	v_mov_b32_e32 v52, v50
	v_mov_b32_e32 v53, v50
	v_mov_b32_e32 v54, v50
	v_mov_b32_e32 v55, v50
	v_mov_b32_e32 v56, v50
	v_mov_b32_e32 v57, v50
	v_mov_b32_e32 v58, v50
	v_mov_b32_e32 v59, v50
	v_mov_b32_e32 v60, v50
	v_mov_b32_e32 v61, v50
	v_mov_b32_e32 v62, v50
	v_mov_b32_e32 v63, v50
	v_mov_b32_e32 v64, v50
	v_mov_b32_e32 v65, v50
	s_branch .Lattn_cont_h1
